# nt hint added to merge-final (MERGED) and out-GEMM epilogue stores
# baseline (speedup 1.0000x reference)
; #define GAS __attribute__((address_space(1)))
; __device__ __forceinline__ float bf_lo(unsigned u) { return __uint_as_float(u << 16); }
; __device__ __forceinline__ float bf_hi(unsigned u) { return __uint_as_float(u & 0xffff0000u); }
; __device__ __forceinline__ float frcp(float x) { return __builtin_amdgcn_rcpf(x); }
; __device__ __forceinline__ v4u pack8(const f32x4 a, const f32x4 b) { v4u w; w.x = cvt_pk_bf16(a[0], a[1]); w.y = cvt_pk_bf16(a[2], a[3]); w.z = cvt_pk_bf16(b[0], b[1]); w.w = cvt_pk_bf16(b[2], b[3]); return w; }
;     __device__ __forceinline__ void operator()(Acc& acc, const Unit& u, int wr, int wc, int fr, int fq, LAS unsigned char* lds) const {
;         const int row0 = u.pm * BM + wr * 64 + fr, c0 = u.pn * BM + wc * 32 + 8 * fq;
;         const GAS bf16* G0 = (const GAS bf16*)(ws + WS_GATE) + (size_t)u.seg * MTOT * 1024; const GAS bf16* G1 = G0 + (size_t)MTOT * 1024; GAS bf16* dst = (GAS bf16*)(ws + WS_MERGED);
;         const bool fin = u.seg == 2;
; #pragma unroll
;         for (int ai = 0; ai < 2; ++ai)
; #pragma unroll
;         for (int mh = 0; mh < 2; ++mh) {
;             v4u ga[2][2], gb[2][2];
; #pragma unroll
;             for (int mm = 0; mm < 2; ++mm)
; #pragma unroll
;                 for (int bj = 0; bj < 2; ++bj) { const size_t ro = (size_t)(row0 + ai * 128 + (2 * mh + mm) * 16) * 1024 + c0 + bj * 128; ga[mm][bj] = *(const GAS v4u*)(G0 + ro); gb[mm][bj] = fin ? ga[mm][bj] : *(const GAS v4u*)(G1 + ro); }
; #pragma unroll
;             for (int mm = 0; mm < 2; ++mm)
; #pragma unroll
;                 for (int bj = 0; bj < 2; ++bj) { const int m = 2 * mh + mm; const v4u x = ga[mm][bj], y = gb[mm][bj];
;                     f32x4 fa0 = {bf_lo(x.x), bf_hi(x.x), bf_lo(x.y), bf_hi(x.y)}, fa1 = {bf_lo(x.z), bf_hi(x.z), bf_lo(x.w), bf_hi(x.w)};
;                     if (!fin) { const f32x4 fb0 = {bf_lo(y.x), bf_hi(y.x), bf_lo(y.y), bf_hi(y.y)}, fb1 = {bf_lo(y.z), bf_hi(y.z), bf_lo(y.w), bf_hi(y.w)};
; #pragma unroll
;                         for (int j = 0; j < 4; ++j) { fa0[j] *= frcp(fb0[j]); fa1[j] *= frcp(fb1[j]); } }
;                     acc[ai][bj][m][0] *= fa0; acc[ai][bj][m][1] *= fa1;
;                     if (fin) *(GAS v4u*)(dst + (size_t)(row0 + ai * 128 + m * 16) * 1024 + c0 + bj * 128) = pack8(acc[ai][bj][m][0], acc[ai][bj][m][1]); }
.Lmg_fin:
	global_load_dwordx4 v[128:131], v182, s[52:53]
	global_load_dwordx4 v[136:139], v182, s[52:53] offset:256
	global_load_dwordx4 v[144:147], v183, s[52:53]
	global_load_dwordx4 v[152:155], v183, s[52:53] offset:256
	global_load_dwordx4 v[218:221], v184, s[52:53]
	global_load_dwordx4 v[226:229], v184, s[52:53] offset:256
	global_load_dwordx4 v[198:201], v185, s[52:53]
	s_waitcnt vmcnt(6)
	v_lshlrev_b32_e32 v206, 16, v128
	v_and_b32_e32 v207, 0xffff0000, v128
	v_lshlrev_b32_e32 v208, 16, v129
	v_and_b32_e32 v209, 0xffff0000, v129
	v_lshlrev_b32_e32 v190, 16, v130
	v_and_b32_e32 v191, 0xffff0000, v130
	v_lshlrev_b32_e32 v192, 16, v131
	v_and_b32_e32 v193, 0xffff0000, v131
	global_load_dwordx4 v[128:131], v185, s[52:53] offset:256
	v_pk_mul_f32 v[124:125], v[124:125], v[206:207]
	v_pk_mul_f32 v[126:127], v[126:127], v[208:209]
	v_pk_mul_f32 v[120:121], v[120:121], v[190:191]
	v_pk_mul_f32 v[122:123], v[122:123], v[192:193]
	v_cvt_pk_bf16_f32 v244, v124, v125
	v_cvt_pk_bf16_f32 v245, v126, v127
	v_cvt_pk_bf16_f32 v246, v120, v121
	v_cvt_pk_bf16_f32 v247, v122, v123
	s_nop 0
	global_store_dwordx4 v182, v[244:247], s[8:9] nt
	s_waitcnt vmcnt(7)
	v_lshlrev_b32_e32 v206, 16, v136
	v_and_b32_e32 v207, 0xffff0000, v136
	v_lshlrev_b32_e32 v208, 16, v137
	v_and_b32_e32 v209, 0xffff0000, v137
	v_lshlrev_b32_e32 v190, 16, v138
	v_and_b32_e32 v191, 0xffff0000, v138
	v_lshlrev_b32_e32 v192, 16, v139
	v_and_b32_e32 v193, 0xffff0000, v139
	global_load_dwordx4 v[136:139], v186, s[52:53]
	v_pk_mul_f32 v[92:93], v[92:93], v[206:207]
	v_pk_mul_f32 v[94:95], v[94:95], v[208:209]
	v_pk_mul_f32 v[88:89], v[88:89], v[190:191]
	v_pk_mul_f32 v[90:91], v[90:91], v[192:193]
	v_cvt_pk_bf16_f32 v248, v92, v93
	v_cvt_pk_bf16_f32 v249, v94, v95
	v_cvt_pk_bf16_f32 v250, v88, v89
	v_cvt_pk_bf16_f32 v251, v90, v91
	s_nop 0
	global_store_dwordx4 v182, v[248:251], s[8:9] offset:256 nt
	s_waitcnt vmcnt(8)
	v_lshlrev_b32_e32 v206, 16, v144
	v_and_b32_e32 v207, 0xffff0000, v144
	v_lshlrev_b32_e32 v208, 16, v145
	v_and_b32_e32 v209, 0xffff0000, v145
	v_lshlrev_b32_e32 v190, 16, v146
	v_and_b32_e32 v191, 0xffff0000, v146
	v_lshlrev_b32_e32 v192, 16, v147
	v_and_b32_e32 v193, 0xffff0000, v147
	global_load_dwordx4 v[144:147], v186, s[52:53] offset:256
	v_pk_mul_f32 v[116:117], v[116:117], v[206:207]
	v_pk_mul_f32 v[118:119], v[118:119], v[208:209]
	v_pk_mul_f32 v[112:113], v[112:113], v[190:191]
	v_pk_mul_f32 v[114:115], v[114:115], v[192:193]
	v_cvt_pk_bf16_f32 v244, v116, v117
	v_cvt_pk_bf16_f32 v245, v118, v119
	v_cvt_pk_bf16_f32 v246, v112, v113
	v_cvt_pk_bf16_f32 v247, v114, v115
	s_nop 0
	global_store_dwordx4 v183, v[244:247], s[8:9] nt
	s_waitcnt vmcnt(9)
	v_lshlrev_b32_e32 v206, 16, v152
	v_and_b32_e32 v207, 0xffff0000, v152
	v_lshlrev_b32_e32 v208, 16, v153
	v_and_b32_e32 v209, 0xffff0000, v153
	v_lshlrev_b32_e32 v190, 16, v154
	v_and_b32_e32 v191, 0xffff0000, v154
	v_lshlrev_b32_e32 v192, 16, v155
	v_and_b32_e32 v193, 0xffff0000, v155
	global_load_dwordx4 v[152:155], v187, s[52:53]
	v_pk_mul_f32 v[84:85], v[84:85], v[206:207]
	v_pk_mul_f32 v[86:87], v[86:87], v[208:209]
	v_pk_mul_f32 v[80:81], v[80:81], v[190:191]
	v_pk_mul_f32 v[82:83], v[82:83], v[192:193]
	v_cvt_pk_bf16_f32 v248, v84, v85
	v_cvt_pk_bf16_f32 v249, v86, v87
	v_cvt_pk_bf16_f32 v250, v80, v81
	v_cvt_pk_bf16_f32 v251, v82, v83
	s_nop 0
	global_store_dwordx4 v183, v[248:251], s[8:9] offset:256 nt
	s_waitcnt vmcnt(10)
	v_lshlrev_b32_e32 v206, 16, v218
	v_and_b32_e32 v207, 0xffff0000, v218
	v_lshlrev_b32_e32 v208, 16, v219
	v_and_b32_e32 v209, 0xffff0000, v219
	v_lshlrev_b32_e32 v190, 16, v220
	v_and_b32_e32 v191, 0xffff0000, v220
	v_lshlrev_b32_e32 v192, 16, v221
	v_and_b32_e32 v193, 0xffff0000, v221
	global_load_dwordx4 v[218:221], v187, s[52:53] offset:256
	v_pk_mul_f32 v[108:109], v[108:109], v[206:207]
	v_pk_mul_f32 v[110:111], v[110:111], v[208:209]
	v_pk_mul_f32 v[104:105], v[104:105], v[190:191]
	v_pk_mul_f32 v[106:107], v[106:107], v[192:193]
	v_cvt_pk_bf16_f32 v244, v108, v109
	v_cvt_pk_bf16_f32 v245, v110, v111
	v_cvt_pk_bf16_f32 v246, v104, v105
	v_cvt_pk_bf16_f32 v247, v106, v107
	s_nop 0
	global_store_dwordx4 v184, v[244:247], s[8:9] nt
	s_waitcnt vmcnt(11)
	v_lshlrev_b32_e32 v206, 16, v226
	v_and_b32_e32 v207, 0xffff0000, v226
	v_lshlrev_b32_e32 v208, 16, v227
	v_and_b32_e32 v209, 0xffff0000, v227
	v_lshlrev_b32_e32 v190, 16, v228
	v_and_b32_e32 v191, 0xffff0000, v228
	v_lshlrev_b32_e32 v192, 16, v229
	v_and_b32_e32 v193, 0xffff0000, v229
	global_load_dwordx4 v[226:229], v188, s[52:53]
	v_pk_mul_f32 v[76:77], v[76:77], v[206:207]
	v_pk_mul_f32 v[78:79], v[78:79], v[208:209]
	v_pk_mul_f32 v[72:73], v[72:73], v[190:191]
	v_pk_mul_f32 v[74:75], v[74:75], v[192:193]
	v_cvt_pk_bf16_f32 v248, v76, v77
	v_cvt_pk_bf16_f32 v249, v78, v79
	v_cvt_pk_bf16_f32 v250, v72, v73
	v_cvt_pk_bf16_f32 v251, v74, v75
	s_nop 0
	global_store_dwordx4 v184, v[248:251], s[8:9] offset:256 nt
	s_waitcnt vmcnt(12)
	v_lshlrev_b32_e32 v206, 16, v198
	v_and_b32_e32 v207, 0xffff0000, v198
	v_lshlrev_b32_e32 v208, 16, v199
	v_and_b32_e32 v209, 0xffff0000, v199
	v_lshlrev_b32_e32 v190, 16, v200
	v_and_b32_e32 v191, 0xffff0000, v200
	v_lshlrev_b32_e32 v192, 16, v201
	v_and_b32_e32 v193, 0xffff0000, v201
	global_load_dwordx4 v[198:201], v188, s[52:53] offset:256
	v_pk_mul_f32 v[100:101], v[100:101], v[206:207]
	v_pk_mul_f32 v[102:103], v[102:103], v[208:209]
	v_pk_mul_f32 v[96:97], v[96:97], v[190:191]
	v_pk_mul_f32 v[98:99], v[98:99], v[192:193]
	v_cvt_pk_bf16_f32 v244, v100, v101
	v_cvt_pk_bf16_f32 v245, v102, v103
	v_cvt_pk_bf16_f32 v246, v96, v97
	v_cvt_pk_bf16_f32 v247, v98, v99
	s_nop 0
	global_store_dwordx4 v185, v[244:247], s[8:9] nt
	s_waitcnt vmcnt(13)
; #define GAS __attribute__((address_space(1)))
; __device__ __forceinline__ float bf_lo(unsigned u) { return __uint_as_float(u << 16); }
; __device__ __forceinline__ float bf_hi(unsigned u) { return __uint_as_float(u & 0xffff0000u); }
; __device__ __forceinline__ float frcp(float x) { return __builtin_amdgcn_rcpf(x); }
; __device__ __forceinline__ v4u pack8(const f32x4 a, const f32x4 b) { v4u w; w.x = cvt_pk_bf16(a[0], a[1]); w.y = cvt_pk_bf16(a[2], a[3]); w.z = cvt_pk_bf16(b[0], b[1]); w.w = cvt_pk_bf16(b[2], b[3]); return w; }
;     __device__ __forceinline__ void operator()(Acc& acc, const Unit& u, int wr, int wc, int fr, int fq, LAS unsigned char* lds) const {
;     ...
;                 for (int bj = 0; bj < 2; ++bj) { const size_t ro = (size_t)(row0 + ai * 128 + (2 * mh + mm) * 16) * 1024 + c0 + bj * 128; ga[mm][bj] = *(const GAS v4u*)(G0 + ro); gb[mm][bj] = fin ? ga[mm][bj] : *(const GAS v4u*)(G1 + ro); }
; #pragma unroll
;             for (int mm = 0; mm < 2; ++mm)
; #pragma unroll
;                 for (int bj = 0; bj < 2; ++bj) { const int m = 2 * mh + mm; const v4u x = ga[mm][bj], y = gb[mm][bj];
;                     f32x4 fa0 = {bf_lo(x.x), bf_hi(x.x), bf_lo(x.y), bf_hi(x.y)}, fa1 = {bf_lo(x.z), bf_hi(x.z), bf_lo(x.w), bf_hi(x.w)};
;                     if (!fin) { const f32x4 fb0 = {bf_lo(y.x), bf_hi(y.x), bf_lo(y.y), bf_hi(y.y)}, fb1 = {bf_lo(y.z), bf_hi(y.z), bf_lo(y.w), bf_hi(y.w)};
; #pragma unroll
;                         for (int j = 0; j < 4; ++j) { fa0[j] *= frcp(fb0[j]); fa1[j] *= frcp(fb1[j]); } }
;                     acc[ai][bj][m][0] *= fa0; acc[ai][bj][m][1] *= fa1;
;                     if (fin) *(GAS v4u*)(dst + (size_t)(row0 + ai * 128 + m * 16) * 1024 + c0 + bj * 128) = pack8(acc[ai][bj][m][0], acc[ai][bj][m][1]); }
	v_lshlrev_b32_e32 v206, 16, v128
	v_and_b32_e32 v207, 0xffff0000, v128
	v_lshlrev_b32_e32 v208, 16, v129
	v_and_b32_e32 v209, 0xffff0000, v129
	v_lshlrev_b32_e32 v190, 16, v130
	v_and_b32_e32 v191, 0xffff0000, v130
	v_lshlrev_b32_e32 v192, 16, v131
	v_and_b32_e32 v193, 0xffff0000, v131
	global_load_dwordx4 v[128:131], v189, s[52:53]
	v_pk_mul_f32 v[68:69], v[68:69], v[206:207]
	v_pk_mul_f32 v[70:71], v[70:71], v[208:209]
	v_pk_mul_f32 v[64:65], v[64:65], v[190:191]
	v_pk_mul_f32 v[66:67], v[66:67], v[192:193]
	v_cvt_pk_bf16_f32 v248, v68, v69
	v_cvt_pk_bf16_f32 v249, v70, v71
	v_cvt_pk_bf16_f32 v250, v64, v65
	v_cvt_pk_bf16_f32 v251, v66, v67
	s_nop 0
	global_store_dwordx4 v185, v[248:251], s[8:9] offset:256 nt
	s_waitcnt vmcnt(13)
	v_lshlrev_b32_e32 v206, 16, v136
	v_and_b32_e32 v207, 0xffff0000, v136
	v_lshlrev_b32_e32 v208, 16, v137
	v_and_b32_e32 v209, 0xffff0000, v137
	v_lshlrev_b32_e32 v190, 16, v138
	v_and_b32_e32 v191, 0xffff0000, v138
	v_lshlrev_b32_e32 v192, 16, v139
	v_and_b32_e32 v193, 0xffff0000, v139
	global_load_dwordx4 v[136:139], v189, s[52:53] offset:256
	v_pk_mul_f32 v[60:61], v[60:61], v[206:207]
	v_pk_mul_f32 v[62:63], v[62:63], v[208:209]
	v_pk_mul_f32 v[56:57], v[56:57], v[190:191]
	v_pk_mul_f32 v[58:59], v[58:59], v[192:193]
	v_cvt_pk_bf16_f32 v244, v60, v61
	v_cvt_pk_bf16_f32 v245, v62, v63
	v_cvt_pk_bf16_f32 v246, v56, v57
	v_cvt_pk_bf16_f32 v247, v58, v59
	s_nop 0
	global_store_dwordx4 v186, v[244:247], s[8:9] nt
	s_waitcnt vmcnt(13)
	v_lshlrev_b32_e32 v206, 16, v144
	v_and_b32_e32 v207, 0xffff0000, v144
	v_lshlrev_b32_e32 v208, 16, v145
	v_and_b32_e32 v209, 0xffff0000, v145
	v_lshlrev_b32_e32 v190, 16, v146
	v_and_b32_e32 v191, 0xffff0000, v146
	v_lshlrev_b32_e32 v192, 16, v147
	v_and_b32_e32 v193, 0xffff0000, v147
	v_pk_mul_f32 v[28:29], v[28:29], v[206:207]
	v_pk_mul_f32 v[30:31], v[30:31], v[208:209]
	v_pk_mul_f32 v[24:25], v[24:25], v[190:191]
	v_pk_mul_f32 v[26:27], v[26:27], v[192:193]
	v_cvt_pk_bf16_f32 v248, v28, v29
	v_cvt_pk_bf16_f32 v249, v30, v31
	v_cvt_pk_bf16_f32 v250, v24, v25
	v_cvt_pk_bf16_f32 v251, v26, v27
	s_nop 0
	global_store_dwordx4 v186, v[248:251], s[8:9] offset:256 nt
	s_waitcnt vmcnt(12)
	v_lshlrev_b32_e32 v206, 16, v152
	v_and_b32_e32 v207, 0xffff0000, v152
	v_lshlrev_b32_e32 v208, 16, v153
	v_and_b32_e32 v209, 0xffff0000, v153
	v_lshlrev_b32_e32 v190, 16, v154
	v_and_b32_e32 v191, 0xffff0000, v154
	v_lshlrev_b32_e32 v192, 16, v155
	v_and_b32_e32 v193, 0xffff0000, v155
	v_pk_mul_f32 v[52:53], v[52:53], v[206:207]
	v_pk_mul_f32 v[54:55], v[54:55], v[208:209]
	v_pk_mul_f32 v[48:49], v[48:49], v[190:191]
	v_pk_mul_f32 v[50:51], v[50:51], v[192:193]
	v_cvt_pk_bf16_f32 v244, v52, v53
	v_cvt_pk_bf16_f32 v245, v54, v55
	v_cvt_pk_bf16_f32 v246, v48, v49
	v_cvt_pk_bf16_f32 v247, v50, v51
	s_nop 0
	global_store_dwordx4 v187, v[244:247], s[8:9] nt
	s_waitcnt vmcnt(11)
	v_lshlrev_b32_e32 v206, 16, v218
	v_and_b32_e32 v207, 0xffff0000, v218
	v_lshlrev_b32_e32 v208, 16, v219
	v_and_b32_e32 v209, 0xffff0000, v219
	v_lshlrev_b32_e32 v190, 16, v220
	v_and_b32_e32 v191, 0xffff0000, v220
	v_lshlrev_b32_e32 v192, 16, v221
	v_and_b32_e32 v193, 0xffff0000, v221
	v_pk_mul_f32 v[20:21], v[20:21], v[206:207]
	v_pk_mul_f32 v[22:23], v[22:23], v[208:209]
	v_pk_mul_f32 v[16:17], v[16:17], v[190:191]
	v_pk_mul_f32 v[18:19], v[18:19], v[192:193]
	v_cvt_pk_bf16_f32 v248, v20, v21
	v_cvt_pk_bf16_f32 v249, v22, v23
	v_cvt_pk_bf16_f32 v250, v16, v17
	v_cvt_pk_bf16_f32 v251, v18, v19
	s_nop 0
	global_store_dwordx4 v187, v[248:251], s[8:9] offset:256 nt
	s_waitcnt vmcnt(10)
	v_lshlrev_b32_e32 v206, 16, v226
	v_and_b32_e32 v207, 0xffff0000, v226
	v_lshlrev_b32_e32 v208, 16, v227
	v_and_b32_e32 v209, 0xffff0000, v227
	v_lshlrev_b32_e32 v190, 16, v228
	v_and_b32_e32 v191, 0xffff0000, v228
	v_lshlrev_b32_e32 v192, 16, v229
	v_and_b32_e32 v193, 0xffff0000, v229
	v_pk_mul_f32 v[44:45], v[44:45], v[206:207]
	v_pk_mul_f32 v[46:47], v[46:47], v[208:209]
	v_pk_mul_f32 v[40:41], v[40:41], v[190:191]
	v_pk_mul_f32 v[42:43], v[42:43], v[192:193]
	v_cvt_pk_bf16_f32 v244, v44, v45
	v_cvt_pk_bf16_f32 v245, v46, v47
	v_cvt_pk_bf16_f32 v246, v40, v41
	v_cvt_pk_bf16_f32 v247, v42, v43
	s_nop 0
	global_store_dwordx4 v188, v[244:247], s[8:9] nt
	s_waitcnt vmcnt(9)
	v_lshlrev_b32_e32 v206, 16, v198
	v_and_b32_e32 v207, 0xffff0000, v198
	v_lshlrev_b32_e32 v208, 16, v199
	v_and_b32_e32 v209, 0xffff0000, v199
	v_lshlrev_b32_e32 v190, 16, v200
	v_and_b32_e32 v191, 0xffff0000, v200
	v_lshlrev_b32_e32 v192, 16, v201
	v_and_b32_e32 v193, 0xffff0000, v201
	v_pk_mul_f32 v[12:13], v[12:13], v[206:207]
	v_pk_mul_f32 v[14:15], v[14:15], v[208:209]
	v_pk_mul_f32 v[8:9], v[8:9], v[190:191]
	v_pk_mul_f32 v[10:11], v[10:11], v[192:193]
	v_cvt_pk_bf16_f32 v248, v12, v13
	v_cvt_pk_bf16_f32 v249, v14, v15
	v_cvt_pk_bf16_f32 v250, v8, v9
	v_cvt_pk_bf16_f32 v251, v10, v11
	s_nop 0
	global_store_dwordx4 v188, v[248:251], s[8:9] offset:256 nt
	s_waitcnt vmcnt(8)
	v_lshlrev_b32_e32 v206, 16, v128
	v_and_b32_e32 v207, 0xffff0000, v128
	v_lshlrev_b32_e32 v208, 16, v129
	v_and_b32_e32 v209, 0xffff0000, v129
	v_lshlrev_b32_e32 v190, 16, v130
	v_and_b32_e32 v191, 0xffff0000, v130
	v_lshlrev_b32_e32 v192, 16, v131
	v_and_b32_e32 v193, 0xffff0000, v131
	v_pk_mul_f32 v[36:37], v[36:37], v[206:207]
	v_pk_mul_f32 v[38:39], v[38:39], v[208:209]
	v_pk_mul_f32 v[32:33], v[32:33], v[190:191]
	v_pk_mul_f32 v[34:35], v[34:35], v[192:193]
	v_cvt_pk_bf16_f32 v244, v36, v37
	v_cvt_pk_bf16_f32 v245, v38, v39
	v_cvt_pk_bf16_f32 v246, v32, v33
	v_cvt_pk_bf16_f32 v247, v34, v35
	s_nop 0
	global_store_dwordx4 v189, v[244:247], s[8:9] nt
	s_waitcnt vmcnt(7)
	v_lshlrev_b32_e32 v206, 16, v136
	v_and_b32_e32 v207, 0xffff0000, v136
	v_lshlrev_b32_e32 v208, 16, v137
	v_and_b32_e32 v209, 0xffff0000, v137
	v_lshlrev_b32_e32 v190, 16, v138
	v_and_b32_e32 v191, 0xffff0000, v138
	v_lshlrev_b32_e32 v192, 16, v139
	v_and_b32_e32 v193, 0xffff0000, v139
	v_pk_mul_f32 v[4:5], v[4:5], v[206:207]
	v_pk_mul_f32 v[6:7], v[6:7], v[208:209]
	v_pk_mul_f32 v[0:1], v[0:1], v[190:191]
	v_pk_mul_f32 v[2:3], v[2:3], v[192:193]
	v_cvt_pk_bf16_f32 v248, v4, v5
	v_cvt_pk_bf16_f32 v249, v6, v7
	v_cvt_pk_bf16_f32 v250, v0, v1
	v_cvt_pk_bf16_f32 v251, v2, v3
	s_nop 0
	global_store_dwordx4 v189, v[248:251], s[8:9] offset:256 nt

; #define GAS __attribute__((address_space(1)))
; __device__ __forceinline__ float bf_lo(unsigned u) { return __uint_as_float(u << 16); }
; __device__ __forceinline__ float bf_hi(unsigned u) { return __uint_as_float(u & 0xffff0000u); }
; __device__ __forceinline__ v4u pack8(const f32x4 a, const f32x4 b) { v4u w; w.x = cvt_pk_bf16(a[0], a[1]); w.y = cvt_pk_bf16(a[2], a[3]); w.z = cvt_pk_bf16(b[0], b[1]); w.w = cvt_pk_bf16(b[2], b[3]); return w; }
;     __device__ __forceinline__ void operator()(Acc& acc, const Unit& u, int wr, int wc, int fr, int fq, LAS unsigned char* lds) const {
;         const int row0 = u.pm * BM + wr * 64 + fr, c0 = u.pn * BM + wc * 32 + 8 * fq; GAS bf16* HB = (GAS bf16*)(ws + WS_H);
;         const bool sample = u.pm >= MPAD / 256;
; #pragma unroll
;         for (int ai = 0; ai < 2; ++ai) {
;             v4u hb[4][2];
; #pragma unroll
;             for (int m = 0; m < 4; ++m)
; #pragma unroll
;                 for (int bj = 0; bj < 2; ++bj) hb[m][bj] = *(const GAS v4u*)(HB + (size_t)(row0 + ai * 128 + m * 16) * 1024 + c0 + bj * 128);
;     ...
;                 } else {
; #pragma unroll
;                     for (int bj = 0; bj < 2; ++bj) { const v4u t = hb[m][bj];
;                         *(GAS v4u*)(HB + (size_t)row * 1024 + c0 + bj * 128) = pack8((f32x4){bf_lo(t.x), bf_hi(t.x), bf_lo(t.y), bf_hi(t.y)} + acc[ai][bj][m][0], (f32x4){bf_lo(t.z), bf_hi(t.z), bf_lo(t.w), bf_hi(t.w)} + acc[ai][bj][m][1]); } } }
.LBB0_1190:
	v_lshl_add_u32 v182, s52, 8, v202
	v_lshl_add_u32 v170, s60, 8, v204
	v_ashrrev_i32_e32 v171, 31, v170
	v_ashrrev_i32_e32 v183, 31, v182
	v_or_b32_e32 v194, 16, v182
	v_lshl_add_u64 v[184:185], v[170:171], 1, s[12:13]
	v_lshlrev_b64 v[128:129], 11, v[182:183]
	v_ashrrev_i32_e32 v195, 31, v194
	v_or_b32_e32 v190, 32, v182
	v_lshl_add_u64 v[198:199], v[184:185], 0, v[128:129]
	v_lshlrev_b64 v[128:129], 11, v[194:195]
	v_ashrrev_i32_e32 v191, 31, v190
	v_or_b32_e32 v186, 48, v182
	v_lshl_add_u64 v[196:197], v[184:185], 0, v[128:129]
	v_lshlrev_b64 v[128:129], 11, v[190:191]
	v_ashrrev_i32_e32 v187, 31, v186
	v_lshl_add_u64 v[192:193], v[184:185], 0, v[128:129]
	v_lshlrev_b64 v[128:129], 11, v[186:187]
	v_lshl_add_u64 v[188:189], v[184:185], 0, v[128:129]
	global_load_dwordx4 v[156:159], v[198:199], off
	global_load_dwordx4 v[152:155], v[198:199], off offset:256
	global_load_dwordx4 v[148:151], v[196:197], off
	global_load_dwordx4 v[144:147], v[196:197], off offset:256
	global_load_dwordx4 v[140:143], v[192:193], off
	global_load_dwordx4 v[136:139], v[192:193], off offset:256
	global_load_dwordx4 v[132:135], v[188:189], off
	global_load_dwordx4 v[128:131], v[188:189], off offset:256
	s_cmpk_lt_i32 s52, 0x41
	s_cselect_b64 s[52:53], -1, 0
	s_andn2_b64 vcc, exec, s[34:35]
	s_mov_b64 s[60:61], -1
	v_readlane_b32 s92, v240, 3
	s_cbranch_vccnz .LBB0_1192
	s_waitcnt vmcnt(0)
	v_lshlrev_b32_e32 v206, 16, v157
	v_and_b32_e32 v207, 0xffff0000, v157
	v_lshlrev_b32_e32 v200, 16, v156
	v_and_b32_e32 v201, 0xffff0000, v156
	v_pk_add_f32 v[208:209], v[126:127], v[206:207]
	v_lshlrev_b32_e32 v206, 16, v158
	v_and_b32_e32 v207, 0xffff0000, v158
	v_lshlrev_b32_e32 v218, 16, v159
	v_and_b32_e32 v219, 0xffff0000, v159
	v_pk_add_f32 v[200:201], v[124:125], v[200:201]
	v_pk_add_f32 v[218:219], v[122:123], v[218:219]
	v_pk_add_f32 v[220:221], v[120:121], v[206:207]
	v_cvt_pk_bf16_f32 v206, v200, v201
	v_cvt_pk_bf16_f32 v207, v208, v209
	v_cvt_pk_bf16_f32 v208, v220, v221
	v_cvt_pk_bf16_f32 v209, v218, v219
	global_store_dwordx4 v[198:199], v[206:209], off nt
	v_lshlrev_b32_e32 v200, 16, v152
	v_and_b32_e32 v201, 0xffff0000, v152
	v_lshlrev_b32_e32 v206, 16, v153
	v_and_b32_e32 v207, 0xffff0000, v153
	v_pk_add_f32 v[208:209], v[118:119], v[206:207]
	v_lshlrev_b32_e32 v206, 16, v154
	v_and_b32_e32 v207, 0xffff0000, v154
	v_lshlrev_b32_e32 v218, 16, v155
	v_and_b32_e32 v219, 0xffff0000, v155
	v_pk_add_f32 v[200:201], v[116:117], v[200:201]
	v_pk_add_f32 v[218:219], v[114:115], v[218:219]
	v_pk_add_f32 v[220:221], v[112:113], v[206:207]
	v_cvt_pk_bf16_f32 v206, v200, v201
	v_cvt_pk_bf16_f32 v207, v208, v209
	v_cvt_pk_bf16_f32 v208, v220, v221
	v_cvt_pk_bf16_f32 v209, v218, v219
	s_mov_b64 s[60:61], 0
	global_store_dwordx4 v[198:199], v[206:209], off offset:256 nt

; #define GAS __attribute__((address_space(1)))
; __device__ __forceinline__ float bf_lo(unsigned u) { return __uint_as_float(u << 16); }
; __device__ __forceinline__ float bf_hi(unsigned u) { return __uint_as_float(u & 0xffff0000u); }
;     __device__ __forceinline__ void operator()(Acc& acc, const Unit& u, int wr, int wc, int fr, int fq, LAS unsigned char* lds) const {
;     ...
;                 if (last) { GAS float* dp; bool ok = true;
;                     if (sample) dp = out + O_YS + (size_t)(row - MPAD) * 1024 + c0;
;                     else { const int b = row / LP, t = row - b * LP; ok = row < MP && t >= NMETA; dp = out + O_YP + ((size_t)b * SEQ + (t - NMETA)) * 1024 + c0; }
;                     if (ok) {
; #pragma unroll
;                         for (int bj = 0; bj < 2; ++bj) { const v4u t = hb[m][bj];
;                             *(GAS f32x4*)(dp + bj * 128) = (f32x4){bf_lo(t.x), bf_hi(t.x), bf_lo(t.y), bf_hi(t.y)} + acc[ai][bj][m][0]; *(GAS f32x4*)(dp + bj * 128 + 4) = (f32x4){bf_lo(t.z), bf_hi(t.z), bf_lo(t.w), bf_hi(t.w)} + acc[ai][bj][m][1]; } }
.LBB0_1196:
	v_ashrrev_i32_e32 v199, 31, v198
	v_lshl_add_u64 v[200:201], s[8:9], 0, v[200:201]
	v_lshlrev_b64 v[198:199], 12, v[198:199]
	v_lshl_add_u64 v[198:199], v[200:201], 0, v[198:199]
	s_waitcnt vmcnt(0)
	v_lshlrev_b32_e32 v200, 16, v156
	v_and_b32_e32 v201, 0xffff0000, v156
	v_lshlrev_b32_e32 v156, 16, v157
	v_and_b32_e32 v157, 0xffff0000, v157
	v_lshl_add_u64 v[198:199], v[170:171], 2, v[198:199]
	v_pk_add_f32 v[126:127], v[126:127], v[156:157]
	v_pk_add_f32 v[124:125], v[124:125], v[200:201]
	global_store_dwordx4 v[198:199], v[124:127], off nt
	s_nop 1
	v_lshlrev_b32_e32 v124, 16, v158
	v_and_b32_e32 v125, 0xffff0000, v158
	v_lshlrev_b32_e32 v126, 16, v159
	v_and_b32_e32 v127, 0xffff0000, v159
	v_pk_add_f32 v[122:123], v[122:123], v[126:127]
	v_pk_add_f32 v[120:121], v[120:121], v[124:125]
	global_store_dwordx4 v[198:199], v[120:123], off offset:16 nt
	s_nop 1
	v_lshlrev_b32_e32 v120, 16, v152
	v_and_b32_e32 v121, 0xffff0000, v152
	v_lshlrev_b32_e32 v122, 16, v153
	v_and_b32_e32 v123, 0xffff0000, v153
	v_pk_add_f32 v[118:119], v[118:119], v[122:123]
	v_pk_add_f32 v[116:117], v[116:117], v[120:121]
	global_store_dwordx4 v[198:199], v[116:119], off offset:512 nt
	s_nop 1
	v_lshlrev_b32_e32 v116, 16, v154
	v_and_b32_e32 v117, 0xffff0000, v154
	v_lshlrev_b32_e32 v118, 16, v155
	v_and_b32_e32 v119, 0xffff0000, v155
	v_pk_add_f32 v[114:115], v[114:115], v[118:119]
	v_pk_add_f32 v[112:113], v[112:113], v[116:117]
	global_store_dwordx4 v[198:199], v[112:115], off offset:528 nt

; #define GAS __attribute__((address_space(1)))
; __device__ __forceinline__ float bf_lo(unsigned u) { return __uint_as_float(u << 16); }
; __device__ __forceinline__ float bf_hi(unsigned u) { return __uint_as_float(u & 0xffff0000u); }
;     __device__ __forceinline__ void operator()(Acc& acc, const Unit& u, int wr, int wc, int fr, int fq, LAS unsigned char* lds) const {
;     ...
;                 if (last) { GAS float* dp; bool ok = true;
;                     if (sample) dp = out + O_YS + (size_t)(row - MPAD) * 1024 + c0;
;                     else { const int b = row / LP, t = row - b * LP; ok = row < MP && t >= NMETA; dp = out + O_YP + ((size_t)b * SEQ + (t - NMETA)) * 1024 + c0; }
;                     if (ok) {
; #pragma unroll
;                         for (int bj = 0; bj < 2; ++bj) { const v4u t = hb[m][bj];
;                             *(GAS f32x4*)(dp + bj * 128) = (f32x4){bf_lo(t.x), bf_hi(t.x), bf_lo(t.y), bf_hi(t.y)} + acc[ai][bj][m][0]; *(GAS f32x4*)(dp + bj * 128 + 4) = (f32x4){bf_lo(t.z), bf_hi(t.z), bf_lo(t.w), bf_hi(t.w)} + acc[ai][bj][m][1]; } }
.LBB0_1202:
	v_ashrrev_i32_e32 v113, 31, v112
	v_lshl_add_u64 v[114:115], s[8:9], 0, v[114:115]
	v_lshlrev_b64 v[112:113], 12, v[112:113]
	v_lshl_add_u64 v[112:113], v[114:115], 0, v[112:113]
	s_waitcnt vmcnt(0)
	v_lshlrev_b32_e32 v114, 16, v148
	v_and_b32_e32 v115, 0xffff0000, v148
	v_lshlrev_b32_e32 v116, 16, v149
	v_and_b32_e32 v117, 0xffff0000, v149
	v_lshl_add_u64 v[112:113], v[170:171], 2, v[112:113]
	v_pk_add_f32 v[110:111], v[110:111], v[116:117]
	v_pk_add_f32 v[108:109], v[108:109], v[114:115]
	global_store_dwordx4 v[112:113], v[108:111], off nt
	s_nop 1
	v_lshlrev_b32_e32 v108, 16, v150
	v_and_b32_e32 v109, 0xffff0000, v150
	v_lshlrev_b32_e32 v110, 16, v151
	v_and_b32_e32 v111, 0xffff0000, v151
	v_pk_add_f32 v[106:107], v[106:107], v[110:111]
	v_pk_add_f32 v[104:105], v[104:105], v[108:109]
	global_store_dwordx4 v[112:113], v[104:107], off offset:16 nt
	s_nop 1
	v_lshlrev_b32_e32 v104, 16, v144
	v_and_b32_e32 v105, 0xffff0000, v144
	v_lshlrev_b32_e32 v106, 16, v145
	v_and_b32_e32 v107, 0xffff0000, v145
	v_pk_add_f32 v[102:103], v[102:103], v[106:107]
	v_pk_add_f32 v[100:101], v[100:101], v[104:105]
	global_store_dwordx4 v[112:113], v[100:103], off offset:512 nt
	s_nop 1
	v_lshlrev_b32_e32 v100, 16, v146
	v_and_b32_e32 v101, 0xffff0000, v146
	v_lshlrev_b32_e32 v102, 16, v147
	v_and_b32_e32 v103, 0xffff0000, v147
	v_pk_add_f32 v[98:99], v[98:99], v[102:103]
	v_pk_add_f32 v[96:97], v[96:97], v[100:101]
	global_store_dwordx4 v[112:113], v[96:99], off offset:528 nt

; #define GAS __attribute__((address_space(1)))
; __device__ __forceinline__ float bf_lo(unsigned u) { return __uint_as_float(u << 16); }
; __device__ __forceinline__ float bf_hi(unsigned u) { return __uint_as_float(u & 0xffff0000u); }
;     __device__ __forceinline__ void operator()(Acc& acc, const Unit& u, int wr, int wc, int fr, int fq, LAS unsigned char* lds) const {
;     ...
;                 if (last) { GAS float* dp; bool ok = true;
;                     if (sample) dp = out + O_YS + (size_t)(row - MPAD) * 1024 + c0;
;                     else { const int b = row / LP, t = row - b * LP; ok = row < MP && t >= NMETA; dp = out + O_YP + ((size_t)b * SEQ + (t - NMETA)) * 1024 + c0; }
;                     if (ok) {
; #pragma unroll
;                         for (int bj = 0; bj < 2; ++bj) { const v4u t = hb[m][bj];
;                             *(GAS f32x4*)(dp + bj * 128) = (f32x4){bf_lo(t.x), bf_hi(t.x), bf_lo(t.y), bf_hi(t.y)} + acc[ai][bj][m][0]; *(GAS f32x4*)(dp + bj * 128 + 4) = (f32x4){bf_lo(t.z), bf_hi(t.z), bf_lo(t.w), bf_hi(t.w)} + acc[ai][bj][m][1]; } }
.LBB0_1208:
	v_ashrrev_i32_e32 v97, 31, v96
	v_lshl_add_u64 v[98:99], s[8:9], 0, v[98:99]
	v_lshlrev_b64 v[96:97], 12, v[96:97]
	v_lshl_add_u64 v[96:97], v[98:99], 0, v[96:97]
	s_waitcnt vmcnt(0)
	v_lshlrev_b32_e32 v98, 16, v140
	v_and_b32_e32 v99, 0xffff0000, v140
	v_lshlrev_b32_e32 v100, 16, v141
	v_and_b32_e32 v101, 0xffff0000, v141
	v_lshl_add_u64 v[96:97], v[170:171], 2, v[96:97]
	v_pk_add_f32 v[94:95], v[94:95], v[100:101]
	v_pk_add_f32 v[92:93], v[92:93], v[98:99]
	global_store_dwordx4 v[96:97], v[92:95], off nt
	s_nop 1
	v_lshlrev_b32_e32 v92, 16, v142
	v_and_b32_e32 v93, 0xffff0000, v142
	v_lshlrev_b32_e32 v94, 16, v143
	v_and_b32_e32 v95, 0xffff0000, v143
	v_pk_add_f32 v[90:91], v[90:91], v[94:95]
	v_pk_add_f32 v[88:89], v[88:89], v[92:93]
	global_store_dwordx4 v[96:97], v[88:91], off offset:16 nt
	s_nop 1
	v_lshlrev_b32_e32 v88, 16, v136
	v_and_b32_e32 v89, 0xffff0000, v136
	v_lshlrev_b32_e32 v90, 16, v137
	v_and_b32_e32 v91, 0xffff0000, v137
	v_pk_add_f32 v[86:87], v[86:87], v[90:91]
	v_pk_add_f32 v[84:85], v[84:85], v[88:89]
	global_store_dwordx4 v[96:97], v[84:87], off offset:512 nt
	s_nop 1
	v_lshlrev_b32_e32 v84, 16, v138
	v_and_b32_e32 v85, 0xffff0000, v138
	v_lshlrev_b32_e32 v86, 16, v139
	v_and_b32_e32 v87, 0xffff0000, v139
	v_pk_add_f32 v[82:83], v[82:83], v[86:87]
	v_pk_add_f32 v[80:81], v[80:81], v[84:85]
	global_store_dwordx4 v[96:97], v[80:83], off offset:528 nt

; #define GAS __attribute__((address_space(1)))
; __device__ __forceinline__ float bf_lo(unsigned u) { return __uint_as_float(u << 16); }
; __device__ __forceinline__ float bf_hi(unsigned u) { return __uint_as_float(u & 0xffff0000u); }
; __device__ __forceinline__ v4u pack8(const f32x4 a, const f32x4 b) { v4u w; w.x = cvt_pk_bf16(a[0], a[1]); w.y = cvt_pk_bf16(a[2], a[3]); w.z = cvt_pk_bf16(b[0], b[1]); w.w = cvt_pk_bf16(b[2], b[3]); return w; }
;     __device__ __forceinline__ void operator()(Acc& acc, const Unit& u, int wr, int wc, int fr, int fq, LAS unsigned char* lds) const {
;     ...
;                 } else {
; #pragma unroll
;                     for (int bj = 0; bj < 2; ++bj) { const v4u t = hb[m][bj];
;                         *(GAS v4u*)(HB + (size_t)row * 1024 + c0 + bj * 128) = pack8((f32x4){bf_lo(t.x), bf_hi(t.x), bf_lo(t.y), bf_hi(t.y)} + acc[ai][bj][m][0], (f32x4){bf_lo(t.z), bf_hi(t.z), bf_lo(t.w), bf_hi(t.w)} + acc[ai][bj][m][1]); } } }
.LBB0_1212:
	s_waitcnt vmcnt(0)
	v_lshlrev_b32_e32 v112, 16, v148
	v_and_b32_e32 v113, 0xffff0000, v148
	v_lshlrev_b32_e32 v114, 16, v149
	v_and_b32_e32 v115, 0xffff0000, v149
	v_lshlrev_b32_e32 v116, 16, v150
	v_and_b32_e32 v117, 0xffff0000, v150
	v_lshlrev_b32_e32 v118, 16, v151
	v_and_b32_e32 v119, 0xffff0000, v151
	v_pk_add_f32 v[114:115], v[110:111], v[114:115]
	v_pk_add_f32 v[112:113], v[108:109], v[112:113]
	v_pk_add_f32 v[118:119], v[106:107], v[118:119]
	v_pk_add_f32 v[116:117], v[104:105], v[116:117]
	v_cvt_pk_bf16_f32 v112, v112, v113
	v_cvt_pk_bf16_f32 v113, v114, v115
	v_cvt_pk_bf16_f32 v114, v116, v117
	v_cvt_pk_bf16_f32 v115, v118, v119
	global_store_dwordx4 v[196:197], v[112:115], off nt
	v_lshlrev_b32_e32 v116, 16, v146
	v_and_b32_e32 v117, 0xffff0000, v146
	v_lshlrev_b32_e32 v112, 16, v144
	v_and_b32_e32 v113, 0xffff0000, v144
	v_lshlrev_b32_e32 v114, 16, v145
	v_and_b32_e32 v115, 0xffff0000, v145
	v_lshlrev_b32_e32 v118, 16, v147
	v_and_b32_e32 v119, 0xffff0000, v147
	v_pk_add_f32 v[114:115], v[102:103], v[114:115]
	v_pk_add_f32 v[112:113], v[100:101], v[112:113]
	v_pk_add_f32 v[118:119], v[98:99], v[118:119]
	v_pk_add_f32 v[116:117], v[96:97], v[116:117]
	v_cvt_pk_bf16_f32 v112, v112, v113
	v_cvt_pk_bf16_f32 v113, v114, v115
	v_cvt_pk_bf16_f32 v114, v116, v117
	v_cvt_pk_bf16_f32 v115, v118, v119
	global_store_dwordx4 v[196:197], v[112:115], off offset:256 nt
	s_nop 1
	v_cndmask_b32_e64 v112, 0, 1, s[52:53]
	v_cmp_ne_u32_e64 s[60:61], 1, v112
	s_cbranch_execz .LBB0_1199

; #define GAS __attribute__((address_space(1)))
; __device__ __forceinline__ float bf_lo(unsigned u) { return __uint_as_float(u << 16); }
; __device__ __forceinline__ float bf_hi(unsigned u) { return __uint_as_float(u & 0xffff0000u); }
; __device__ __forceinline__ v4u pack8(const f32x4 a, const f32x4 b) { v4u w; w.x = cvt_pk_bf16(a[0], a[1]); w.y = cvt_pk_bf16(a[2], a[3]); w.z = cvt_pk_bf16(b[0], b[1]); w.w = cvt_pk_bf16(b[2], b[3]); return w; }
;     __device__ __forceinline__ void operator()(Acc& acc, const Unit& u, int wr, int wc, int fr, int fq, LAS unsigned char* lds) const {
;     ...
;                 } else {
; #pragma unroll
;                     for (int bj = 0; bj < 2; ++bj) { const v4u t = hb[m][bj];
;                         *(GAS v4u*)(HB + (size_t)row * 1024 + c0 + bj * 128) = pack8((f32x4){bf_lo(t.x), bf_hi(t.x), bf_lo(t.y), bf_hi(t.y)} + acc[ai][bj][m][0], (f32x4){bf_lo(t.z), bf_hi(t.z), bf_lo(t.w), bf_hi(t.w)} + acc[ai][bj][m][1]); } } }
.LBB0_1214:
	s_waitcnt vmcnt(0)
	v_lshlrev_b32_e32 v96, 16, v140
	v_and_b32_e32 v97, 0xffff0000, v140
	v_lshlrev_b32_e32 v98, 16, v141
	v_and_b32_e32 v99, 0xffff0000, v141
	v_lshlrev_b32_e32 v100, 16, v142
	v_and_b32_e32 v101, 0xffff0000, v142
	v_lshlrev_b32_e32 v102, 16, v143
	v_and_b32_e32 v103, 0xffff0000, v143
	v_pk_add_f32 v[98:99], v[94:95], v[98:99]
	v_pk_add_f32 v[96:97], v[92:93], v[96:97]
	v_pk_add_f32 v[102:103], v[90:91], v[102:103]
	v_pk_add_f32 v[100:101], v[88:89], v[100:101]
	v_cvt_pk_bf16_f32 v96, v96, v97
	v_cvt_pk_bf16_f32 v97, v98, v99
	v_cvt_pk_bf16_f32 v98, v100, v101
	v_cvt_pk_bf16_f32 v99, v102, v103
	global_store_dwordx4 v[192:193], v[96:99], off nt
	v_lshlrev_b32_e32 v100, 16, v138
	v_and_b32_e32 v101, 0xffff0000, v138
	v_lshlrev_b32_e32 v96, 16, v136
	v_and_b32_e32 v97, 0xffff0000, v136
	v_lshlrev_b32_e32 v98, 16, v137
	v_and_b32_e32 v99, 0xffff0000, v137
	v_lshlrev_b32_e32 v102, 16, v139
	v_and_b32_e32 v103, 0xffff0000, v139
	v_pk_add_f32 v[98:99], v[86:87], v[98:99]
	v_pk_add_f32 v[96:97], v[84:85], v[96:97]
	v_pk_add_f32 v[102:103], v[82:83], v[102:103]
	v_pk_add_f32 v[100:101], v[80:81], v[100:101]
	v_cvt_pk_bf16_f32 v96, v96, v97
	v_cvt_pk_bf16_f32 v97, v98, v99
	v_cvt_pk_bf16_f32 v98, v100, v101
	v_cvt_pk_bf16_f32 v99, v102, v103
	global_store_dwordx4 v[192:193], v[96:99], off offset:256 nt
	s_cbranch_execz .LBB0_1205

; #define GAS __attribute__((address_space(1)))
; __device__ __forceinline__ float bf_lo(unsigned u) { return __uint_as_float(u << 16); }
; __device__ __forceinline__ float bf_hi(unsigned u) { return __uint_as_float(u & 0xffff0000u); }
; __device__ __forceinline__ v4u pack8(const f32x4 a, const f32x4 b) { v4u w; w.x = cvt_pk_bf16(a[0], a[1]); w.y = cvt_pk_bf16(a[2], a[3]); w.z = cvt_pk_bf16(b[0], b[1]); w.w = cvt_pk_bf16(b[2], b[3]); return w; }
;     __device__ __forceinline__ void operator()(Acc& acc, const Unit& u, int wr, int wc, int fr, int fq, LAS unsigned char* lds) const {
;     ...
;                 } else {
; #pragma unroll
;                     for (int bj = 0; bj < 2; ++bj) { const v4u t = hb[m][bj];
;                         *(GAS v4u*)(HB + (size_t)row * 1024 + c0 + bj * 128) = pack8((f32x4){bf_lo(t.x), bf_hi(t.x), bf_lo(t.y), bf_hi(t.y)} + acc[ai][bj][m][0], (f32x4){bf_lo(t.z), bf_hi(t.z), bf_lo(t.w), bf_hi(t.w)} + acc[ai][bj][m][1]); } } }
.LBB0_1216:
	s_waitcnt vmcnt(0)
	v_lshlrev_b32_e32 v80, 16, v132
	v_and_b32_e32 v81, 0xffff0000, v132
	v_lshlrev_b32_e32 v82, 16, v133
	v_and_b32_e32 v83, 0xffff0000, v133
	v_lshlrev_b32_e32 v84, 16, v134
	v_and_b32_e32 v85, 0xffff0000, v134
	v_lshlrev_b32_e32 v86, 16, v135
	v_and_b32_e32 v87, 0xffff0000, v135
	v_pk_add_f32 v[82:83], v[78:79], v[82:83]
	v_pk_add_f32 v[80:81], v[76:77], v[80:81]
	v_pk_add_f32 v[86:87], v[74:75], v[86:87]
	v_pk_add_f32 v[84:85], v[72:73], v[84:85]
	v_cvt_pk_bf16_f32 v80, v80, v81
	v_cvt_pk_bf16_f32 v81, v82, v83
	v_cvt_pk_bf16_f32 v82, v84, v85
	v_cvt_pk_bf16_f32 v83, v86, v87
	global_store_dwordx4 v[188:189], v[80:83], off nt
	v_lshlrev_b32_e32 v84, 16, v130
	v_and_b32_e32 v85, 0xffff0000, v130
	v_lshlrev_b32_e32 v80, 16, v128
	v_and_b32_e32 v81, 0xffff0000, v128
	v_lshlrev_b32_e32 v82, 16, v129
	v_and_b32_e32 v83, 0xffff0000, v129
	v_lshlrev_b32_e32 v86, 16, v131
	v_and_b32_e32 v87, 0xffff0000, v131
	v_pk_add_f32 v[82:83], v[70:71], v[82:83]
	v_pk_add_f32 v[80:81], v[68:69], v[80:81]
	v_pk_add_f32 v[86:87], v[66:67], v[86:87]
	v_pk_add_f32 v[84:85], v[64:65], v[84:85]
	v_cvt_pk_bf16_f32 v80, v80, v81
	v_cvt_pk_bf16_f32 v81, v82, v83
	v_cvt_pk_bf16_f32 v82, v84, v85
	v_cvt_pk_bf16_f32 v83, v86, v87
	global_store_dwordx4 v[188:189], v[80:83], off offset:256 nt
	s_cbranch_execnz .LBB0_1222

; #define GAS __attribute__((address_space(1)))
; __device__ __forceinline__ float bf_lo(unsigned u) { return __uint_as_float(u << 16); }
; __device__ __forceinline__ float bf_hi(unsigned u) { return __uint_as_float(u & 0xffff0000u); }
;     __device__ __forceinline__ void operator()(Acc& acc, const Unit& u, int wr, int wc, int fr, int fq, LAS unsigned char* lds) const {
;     ...
;                 if (last) { GAS float* dp; bool ok = true;
;                     if (sample) dp = out + O_YS + (size_t)(row - MPAD) * 1024 + c0;
;                     else { const int b = row / LP, t = row - b * LP; ok = row < MP && t >= NMETA; dp = out + O_YP + ((size_t)b * SEQ + (t - NMETA)) * 1024 + c0; }
;                     if (ok) {
; #pragma unroll
;                         for (int bj = 0; bj < 2; ++bj) { const v4u t = hb[m][bj];
;                             *(GAS f32x4*)(dp + bj * 128) = (f32x4){bf_lo(t.x), bf_hi(t.x), bf_lo(t.y), bf_hi(t.y)} + acc[ai][bj][m][0]; *(GAS f32x4*)(dp + bj * 128 + 4) = (f32x4){bf_lo(t.z), bf_hi(t.z), bf_lo(t.w), bf_hi(t.w)} + acc[ai][bj][m][1]; } }
.LBB0_1220:
	v_ashrrev_i32_e32 v81, 31, v80
	v_lshl_add_u64 v[82:83], s[8:9], 0, v[82:83]
	v_lshlrev_b64 v[80:81], 12, v[80:81]
	v_lshl_add_u64 v[80:81], v[82:83], 0, v[80:81]
	s_waitcnt vmcnt(0)
	v_lshlrev_b32_e32 v82, 16, v132
	v_and_b32_e32 v83, 0xffff0000, v132
	v_lshlrev_b32_e32 v84, 16, v133
	v_and_b32_e32 v85, 0xffff0000, v133
	v_lshl_add_u64 v[80:81], v[170:171], 2, v[80:81]
	v_pk_add_f32 v[78:79], v[78:79], v[84:85]
	v_pk_add_f32 v[76:77], v[76:77], v[82:83]
	global_store_dwordx4 v[80:81], v[76:79], off nt
	s_nop 1
	v_lshlrev_b32_e32 v76, 16, v134
	v_and_b32_e32 v77, 0xffff0000, v134
	v_lshlrev_b32_e32 v78, 16, v135
	v_and_b32_e32 v79, 0xffff0000, v135
	v_pk_add_f32 v[74:75], v[74:75], v[78:79]
	v_pk_add_f32 v[72:73], v[72:73], v[76:77]
	global_store_dwordx4 v[80:81], v[72:75], off offset:16 nt
	s_nop 1
	v_lshlrev_b32_e32 v72, 16, v128
	v_and_b32_e32 v73, 0xffff0000, v128
	v_lshlrev_b32_e32 v74, 16, v129
	v_and_b32_e32 v75, 0xffff0000, v129
	v_pk_add_f32 v[70:71], v[70:71], v[74:75]
	v_pk_add_f32 v[68:69], v[68:69], v[72:73]
	global_store_dwordx4 v[80:81], v[68:71], off offset:512 nt
	s_nop 1
	v_lshlrev_b32_e32 v68, 16, v130
	v_and_b32_e32 v69, 0xffff0000, v130
	v_lshlrev_b32_e32 v70, 16, v131
	v_and_b32_e32 v71, 0xffff0000, v131
	v_pk_add_f32 v[66:67], v[66:67], v[70:71]
	v_pk_add_f32 v[64:65], v[64:65], v[68:69]
	global_store_dwordx4 v[80:81], v[64:67], off offset:528 nt

; #define GAS __attribute__((address_space(1)))
; __device__ __forceinline__ float bf_lo(unsigned u) { return __uint_as_float(u << 16); }
; __device__ __forceinline__ float bf_hi(unsigned u) { return __uint_as_float(u & 0xffff0000u); }
; __device__ __forceinline__ v4u pack8(const f32x4 a, const f32x4 b) { v4u w; w.x = cvt_pk_bf16(a[0], a[1]); w.y = cvt_pk_bf16(a[2], a[3]); w.z = cvt_pk_bf16(b[0], b[1]); w.w = cvt_pk_bf16(b[2], b[3]); return w; }
;     __device__ __forceinline__ void operator()(Acc& acc, const Unit& u, int wr, int wc, int fr, int fq, LAS unsigned char* lds) const {
;     ...
;         for (int ai = 0; ai < 2; ++ai) {
;             v4u hb[4][2];
; #pragma unroll
;             for (int m = 0; m < 4; ++m)
; #pragma unroll
;                 for (int bj = 0; bj < 2; ++bj) hb[m][bj] = *(const GAS v4u*)(HB + (size_t)(row0 + ai * 128 + m * 16) * 1024 + c0 + bj * 128);
;     ...
;                 } else {
; #pragma unroll
;                     for (int bj = 0; bj < 2; ++bj) { const v4u t = hb[m][bj];
;                         *(GAS v4u*)(HB + (size_t)row * 1024 + c0 + bj * 128) = pack8((f32x4){bf_lo(t.x), bf_hi(t.x), bf_lo(t.y), bf_hi(t.y)} + acc[ai][bj][m][0], (f32x4){bf_lo(t.z), bf_hi(t.z), bf_lo(t.w), bf_hi(t.w)} + acc[ai][bj][m][1]); } } }
.LBB0_1222:
	v_add_u32_e32 v108, 0x80, v182
	v_ashrrev_i32_e32 v109, 31, v108
	v_add_u32_e32 v104, 0x90, v182
	v_lshlrev_b64 v[64:65], 11, v[108:109]
	v_ashrrev_i32_e32 v105, 31, v104
	v_add_u32_e32 v100, 0xa0, v182
	v_lshl_add_u64 v[110:111], v[184:185], 0, v[64:65]
	v_lshlrev_b64 v[64:65], 11, v[104:105]
	v_ashrrev_i32_e32 v101, 31, v100
	v_add_u32_e32 v96, 0xb0, v182
	v_lshl_add_u64 v[106:107], v[184:185], 0, v[64:65]
	v_lshlrev_b64 v[64:65], 11, v[100:101]
	v_ashrrev_i32_e32 v97, 31, v96
	v_lshl_add_u64 v[102:103], v[184:185], 0, v[64:65]
	v_lshlrev_b64 v[64:65], 11, v[96:97]
	v_lshl_add_u64 v[98:99], v[184:185], 0, v[64:65]
	global_load_dwordx4 v[92:95], v[110:111], off
	global_load_dwordx4 v[88:91], v[110:111], off offset:256
	global_load_dwordx4 v[84:87], v[106:107], off
	global_load_dwordx4 v[80:83], v[106:107], off offset:256
	global_load_dwordx4 v[76:79], v[102:103], off
	global_load_dwordx4 v[72:75], v[102:103], off offset:256
	global_load_dwordx4 v[68:71], v[98:99], off
	global_load_dwordx4 v[64:67], v[98:99], off offset:256
	s_mov_b64 s[52:53], -1
	s_and_b64 vcc, exec, s[34:35]
	s_cbranch_vccz .LBB0_1231
	s_waitcnt vmcnt(0)
	v_lshlrev_b32_e32 v112, 16, v92
	v_and_b32_e32 v113, 0xffff0000, v92
	v_lshlrev_b32_e32 v114, 16, v93
	v_and_b32_e32 v115, 0xffff0000, v93
	v_lshlrev_b32_e32 v116, 16, v94
	v_and_b32_e32 v117, 0xffff0000, v94
	v_lshlrev_b32_e32 v118, 16, v95
	v_and_b32_e32 v119, 0xffff0000, v95
	v_pk_add_f32 v[114:115], v[62:63], v[114:115]
	v_pk_add_f32 v[112:113], v[60:61], v[112:113]
	v_pk_add_f32 v[118:119], v[58:59], v[118:119]
	v_pk_add_f32 v[116:117], v[56:57], v[116:117]
	v_cvt_pk_bf16_f32 v112, v112, v113
	v_cvt_pk_bf16_f32 v113, v114, v115
	v_cvt_pk_bf16_f32 v114, v116, v117
	v_cvt_pk_bf16_f32 v115, v118, v119
	global_store_dwordx4 v[110:111], v[112:115], off nt
	v_lshlrev_b32_e32 v116, 16, v90
	v_and_b32_e32 v117, 0xffff0000, v90
	v_lshlrev_b32_e32 v112, 16, v88
	v_and_b32_e32 v113, 0xffff0000, v88
	v_lshlrev_b32_e32 v114, 16, v89
	v_and_b32_e32 v115, 0xffff0000, v89
	v_lshlrev_b32_e32 v118, 16, v91
	v_and_b32_e32 v119, 0xffff0000, v91
	v_pk_add_f32 v[114:115], v[54:55], v[114:115]
	v_pk_add_f32 v[112:113], v[52:53], v[112:113]
	v_pk_add_f32 v[118:119], v[50:51], v[118:119]
	v_pk_add_f32 v[116:117], v[48:49], v[116:117]
	v_cvt_pk_bf16_f32 v112, v112, v113
	v_cvt_pk_bf16_f32 v113, v114, v115
	v_cvt_pk_bf16_f32 v114, v116, v117
	v_cvt_pk_bf16_f32 v115, v118, v119
	global_store_dwordx4 v[110:111], v[112:115], off offset:256 nt
	s_cbranch_execz .LBB0_1232

; #define GAS __attribute__((address_space(1)))
; __device__ __forceinline__ float bf_lo(unsigned u) { return __uint_as_float(u << 16); }
; __device__ __forceinline__ float bf_hi(unsigned u) { return __uint_as_float(u & 0xffff0000u); }
; __device__ __forceinline__ v4u pack8(const f32x4 a, const f32x4 b) { v4u w; w.x = cvt_pk_bf16(a[0], a[1]); w.y = cvt_pk_bf16(a[2], a[3]); w.z = cvt_pk_bf16(b[0], b[1]); w.w = cvt_pk_bf16(b[2], b[3]); return w; }
;     __device__ __forceinline__ void operator()(Acc& acc, const Unit& u, int wr, int wc, int fr, int fq, LAS unsigned char* lds) const {
;     ...
;                 } else {
; #pragma unroll
;                     for (int bj = 0; bj < 2; ++bj) { const v4u t = hb[m][bj];
;                         *(GAS v4u*)(HB + (size_t)row * 1024 + c0 + bj * 128) = pack8((f32x4){bf_lo(t.x), bf_hi(t.x), bf_lo(t.y), bf_hi(t.y)} + acc[ai][bj][m][0], (f32x4){bf_lo(t.z), bf_hi(t.z), bf_lo(t.w), bf_hi(t.w)} + acc[ai][bj][m][1]); } } }
.LBB0_1225:
	s_waitcnt vmcnt(0)
	v_lshlrev_b32_e32 v48, 16, v84
	v_and_b32_e32 v49, 0xffff0000, v84
	v_lshlrev_b32_e32 v50, 16, v85
	v_and_b32_e32 v51, 0xffff0000, v85
	v_lshlrev_b32_e32 v52, 16, v86
	v_and_b32_e32 v53, 0xffff0000, v86
	v_lshlrev_b32_e32 v54, 16, v87
	v_and_b32_e32 v55, 0xffff0000, v87
	v_pk_add_f32 v[50:51], v[46:47], v[50:51]
	v_pk_add_f32 v[48:49], v[44:45], v[48:49]
	v_pk_add_f32 v[54:55], v[42:43], v[54:55]
	v_pk_add_f32 v[52:53], v[40:41], v[52:53]
	v_cvt_pk_bf16_f32 v48, v48, v49
	v_cvt_pk_bf16_f32 v49, v50, v51
	v_cvt_pk_bf16_f32 v50, v52, v53
	v_cvt_pk_bf16_f32 v51, v54, v55
	global_store_dwordx4 v[106:107], v[48:51], off nt
	v_lshlrev_b32_e32 v52, 16, v82
	v_and_b32_e32 v53, 0xffff0000, v82
	v_lshlrev_b32_e32 v48, 16, v80
	v_and_b32_e32 v49, 0xffff0000, v80
	v_lshlrev_b32_e32 v50, 16, v81
	v_and_b32_e32 v51, 0xffff0000, v81
	v_lshlrev_b32_e32 v54, 16, v83
	v_and_b32_e32 v55, 0xffff0000, v83
	v_pk_add_f32 v[50:51], v[38:39], v[50:51]
	v_pk_add_f32 v[48:49], v[36:37], v[48:49]
	v_pk_add_f32 v[54:55], v[34:35], v[54:55]
	v_pk_add_f32 v[52:53], v[32:33], v[52:53]
	v_cvt_pk_bf16_f32 v48, v48, v49
	v_cvt_pk_bf16_f32 v49, v50, v51
	v_cvt_pk_bf16_f32 v50, v52, v53
	v_cvt_pk_bf16_f32 v51, v54, v55
	global_store_dwordx4 v[106:107], v[48:51], off offset:256 nt
	s_cbranch_execz .LBB0_1238

; #define GAS __attribute__((address_space(1)))
; __device__ __forceinline__ float bf_lo(unsigned u) { return __uint_as_float(u << 16); }
; __device__ __forceinline__ float bf_hi(unsigned u) { return __uint_as_float(u & 0xffff0000u); }
; __device__ __forceinline__ v4u pack8(const f32x4 a, const f32x4 b) { v4u w; w.x = cvt_pk_bf16(a[0], a[1]); w.y = cvt_pk_bf16(a[2], a[3]); w.z = cvt_pk_bf16(b[0], b[1]); w.w = cvt_pk_bf16(b[2], b[3]); return w; }
;     __device__ __forceinline__ void operator()(Acc& acc, const Unit& u, int wr, int wc, int fr, int fq, LAS unsigned char* lds) const {
;     ...
;                 } else {
; #pragma unroll
;                     for (int bj = 0; bj < 2; ++bj) { const v4u t = hb[m][bj];
;                         *(GAS v4u*)(HB + (size_t)row * 1024 + c0 + bj * 128) = pack8((f32x4){bf_lo(t.x), bf_hi(t.x), bf_lo(t.y), bf_hi(t.y)} + acc[ai][bj][m][0], (f32x4){bf_lo(t.z), bf_hi(t.z), bf_lo(t.w), bf_hi(t.w)} + acc[ai][bj][m][1]); } } }
.LBB0_1227:
	s_waitcnt vmcnt(0)
	v_lshlrev_b32_e32 v32, 16, v76
	v_and_b32_e32 v33, 0xffff0000, v76
	v_lshlrev_b32_e32 v34, 16, v77
	v_and_b32_e32 v35, 0xffff0000, v77
	v_lshlrev_b32_e32 v36, 16, v78
	v_and_b32_e32 v37, 0xffff0000, v78
	v_lshlrev_b32_e32 v38, 16, v79
	v_and_b32_e32 v39, 0xffff0000, v79
	v_pk_add_f32 v[34:35], v[30:31], v[34:35]
	v_pk_add_f32 v[32:33], v[28:29], v[32:33]
	v_pk_add_f32 v[38:39], v[26:27], v[38:39]
	v_pk_add_f32 v[36:37], v[24:25], v[36:37]
	v_cvt_pk_bf16_f32 v32, v32, v33
	v_cvt_pk_bf16_f32 v33, v34, v35
	v_cvt_pk_bf16_f32 v34, v36, v37
	v_cvt_pk_bf16_f32 v35, v38, v39
	global_store_dwordx4 v[102:103], v[32:35], off nt
	v_lshlrev_b32_e32 v36, 16, v74
	v_and_b32_e32 v37, 0xffff0000, v74
	v_lshlrev_b32_e32 v32, 16, v72
	v_and_b32_e32 v33, 0xffff0000, v72
	v_lshlrev_b32_e32 v34, 16, v73
	v_and_b32_e32 v35, 0xffff0000, v73
	v_lshlrev_b32_e32 v38, 16, v75
	v_and_b32_e32 v39, 0xffff0000, v75
	v_pk_add_f32 v[34:35], v[22:23], v[34:35]
	v_pk_add_f32 v[32:33], v[20:21], v[32:33]
	v_pk_add_f32 v[38:39], v[18:19], v[38:39]
	v_pk_add_f32 v[36:37], v[16:17], v[36:37]
	v_cvt_pk_bf16_f32 v32, v32, v33
	v_cvt_pk_bf16_f32 v33, v34, v35
	v_cvt_pk_bf16_f32 v34, v36, v37
	v_cvt_pk_bf16_f32 v35, v38, v39
	global_store_dwordx4 v[102:103], v[32:35], off offset:256 nt
	s_cbranch_execz .LBB0_1244

; #define GAS __attribute__((address_space(1)))
; __device__ __forceinline__ float bf_lo(unsigned u) { return __uint_as_float(u << 16); }
; __device__ __forceinline__ float bf_hi(unsigned u) { return __uint_as_float(u & 0xffff0000u); }
; __device__ __forceinline__ v4u pack8(const f32x4 a, const f32x4 b) { v4u w; w.x = cvt_pk_bf16(a[0], a[1]); w.y = cvt_pk_bf16(a[2], a[3]); w.z = cvt_pk_bf16(b[0], b[1]); w.w = cvt_pk_bf16(b[2], b[3]); return w; }
;     __device__ __forceinline__ void operator()(Acc& acc, const Unit& u, int wr, int wc, int fr, int fq, LAS unsigned char* lds) const {
;     ...
;                 } else {
; #pragma unroll
;                     for (int bj = 0; bj < 2; ++bj) { const v4u t = hb[m][bj];
;                         *(GAS v4u*)(HB + (size_t)row * 1024 + c0 + bj * 128) = pack8((f32x4){bf_lo(t.x), bf_hi(t.x), bf_lo(t.y), bf_hi(t.y)} + acc[ai][bj][m][0], (f32x4){bf_lo(t.z), bf_hi(t.z), bf_lo(t.w), bf_hi(t.w)} + acc[ai][bj][m][1]); } } }
.LBB0_1229:
	s_waitcnt vmcnt(0)
	v_lshlrev_b32_e32 v16, 16, v68
	v_and_b32_e32 v17, 0xffff0000, v68
	v_lshlrev_b32_e32 v18, 16, v69
	v_and_b32_e32 v19, 0xffff0000, v69
	v_lshlrev_b32_e32 v20, 16, v70
	v_and_b32_e32 v21, 0xffff0000, v70
	v_lshlrev_b32_e32 v22, 16, v71
	v_and_b32_e32 v23, 0xffff0000, v71
	v_pk_add_f32 v[18:19], v[14:15], v[18:19]
	v_pk_add_f32 v[16:17], v[12:13], v[16:17]
	v_pk_add_f32 v[22:23], v[10:11], v[22:23]
	v_pk_add_f32 v[20:21], v[8:9], v[20:21]
	v_cvt_pk_bf16_f32 v16, v16, v17
	v_cvt_pk_bf16_f32 v17, v18, v19
	v_cvt_pk_bf16_f32 v18, v20, v21
	v_cvt_pk_bf16_f32 v19, v22, v23
	global_store_dwordx4 v[98:99], v[16:19], off nt
	v_lshlrev_b32_e32 v20, 16, v66
	v_and_b32_e32 v21, 0xffff0000, v66
	v_lshlrev_b32_e32 v16, 16, v64
	v_and_b32_e32 v17, 0xffff0000, v64
	v_lshlrev_b32_e32 v18, 16, v65
	v_and_b32_e32 v19, 0xffff0000, v65
	v_lshlrev_b32_e32 v22, 16, v67
	v_and_b32_e32 v23, 0xffff0000, v67
	v_pk_add_f32 v[18:19], v[6:7], v[18:19]
	v_pk_add_f32 v[16:17], v[4:5], v[16:17]
	v_pk_add_f32 v[22:23], v[2:3], v[22:23]
	v_pk_add_f32 v[20:21], v[0:1], v[20:21]
	v_cvt_pk_bf16_f32 v16, v16, v17
	v_cvt_pk_bf16_f32 v17, v18, v19
	v_cvt_pk_bf16_f32 v18, v20, v21
	v_cvt_pk_bf16_f32 v19, v22, v23
	global_store_dwordx4 v[98:99], v[16:19], off offset:256 nt
	s_cbranch_execz .LBB0_1250

; #define GAS __attribute__((address_space(1)))
; __device__ __forceinline__ float bf_lo(unsigned u) { return __uint_as_float(u << 16); }
; __device__ __forceinline__ float bf_hi(unsigned u) { return __uint_as_float(u & 0xffff0000u); }
;     __device__ __forceinline__ void operator()(Acc& acc, const Unit& u, int wr, int wc, int fr, int fq, LAS unsigned char* lds) const {
;     ...
;                 if (last) { GAS float* dp; bool ok = true;
;                     if (sample) dp = out + O_YS + (size_t)(row - MPAD) * 1024 + c0;
;                     else { const int b = row / LP, t = row - b * LP; ok = row < MP && t >= NMETA; dp = out + O_YP + ((size_t)b * SEQ + (t - NMETA)) * 1024 + c0; }
;                     if (ok) {
; #pragma unroll
;                         for (int bj = 0; bj < 2; ++bj) { const v4u t = hb[m][bj];
;                             *(GAS f32x4*)(dp + bj * 128) = (f32x4){bf_lo(t.x), bf_hi(t.x), bf_lo(t.y), bf_hi(t.y)} + acc[ai][bj][m][0]; *(GAS f32x4*)(dp + bj * 128 + 4) = (f32x4){bf_lo(t.z), bf_hi(t.z), bf_lo(t.w), bf_hi(t.w)} + acc[ai][bj][m][1]; } }
.LBB0_1235:
	v_ashrrev_i32_e32 v111, 31, v110
	v_lshl_add_u64 v[108:109], s[8:9], 0, v[112:113]
	v_lshlrev_b64 v[110:111], 12, v[110:111]
	v_lshl_add_u64 v[108:109], v[108:109], 0, v[110:111]
	s_waitcnt vmcnt(0)
	v_lshlrev_b32_e32 v110, 16, v92
	v_and_b32_e32 v111, 0xffff0000, v92
	v_lshlrev_b32_e32 v92, 16, v93
	v_and_b32_e32 v93, 0xffff0000, v93
	v_lshl_add_u64 v[108:109], v[170:171], 2, v[108:109]
	v_pk_add_f32 v[62:63], v[62:63], v[92:93]
	v_pk_add_f32 v[60:61], v[60:61], v[110:111]
	global_store_dwordx4 v[108:109], v[60:63], off nt
	s_nop 1
	v_lshlrev_b32_e32 v60, 16, v94
	v_and_b32_e32 v61, 0xffff0000, v94
	v_lshlrev_b32_e32 v62, 16, v95
	v_and_b32_e32 v63, 0xffff0000, v95
	v_pk_add_f32 v[58:59], v[58:59], v[62:63]
	v_pk_add_f32 v[56:57], v[56:57], v[60:61]
	global_store_dwordx4 v[108:109], v[56:59], off offset:16 nt
	s_nop 1
	v_lshlrev_b32_e32 v56, 16, v88
	v_and_b32_e32 v57, 0xffff0000, v88
	v_lshlrev_b32_e32 v58, 16, v89
	v_and_b32_e32 v59, 0xffff0000, v89
	v_pk_add_f32 v[54:55], v[54:55], v[58:59]
	v_pk_add_f32 v[52:53], v[52:53], v[56:57]
	global_store_dwordx4 v[108:109], v[52:55], off offset:512 nt
	s_nop 1
	v_lshlrev_b32_e32 v52, 16, v90
	v_and_b32_e32 v53, 0xffff0000, v90
	v_lshlrev_b32_e32 v54, 16, v91
	v_and_b32_e32 v55, 0xffff0000, v91
	v_pk_add_f32 v[50:51], v[50:51], v[54:55]
	v_pk_add_f32 v[48:49], v[48:49], v[52:53]
	global_store_dwordx4 v[108:109], v[48:51], off offset:528 nt

; #define GAS __attribute__((address_space(1)))
; __device__ __forceinline__ float bf_lo(unsigned u) { return __uint_as_float(u << 16); }
; __device__ __forceinline__ float bf_hi(unsigned u) { return __uint_as_float(u & 0xffff0000u); }
;     __device__ __forceinline__ void operator()(Acc& acc, const Unit& u, int wr, int wc, int fr, int fq, LAS unsigned char* lds) const {
;     ...
;                 if (last) { GAS float* dp; bool ok = true;
;                     if (sample) dp = out + O_YS + (size_t)(row - MPAD) * 1024 + c0;
;                     else { const int b = row / LP, t = row - b * LP; ok = row < MP && t >= NMETA; dp = out + O_YP + ((size_t)b * SEQ + (t - NMETA)) * 1024 + c0; }
;                     if (ok) {
; #pragma unroll
;                         for (int bj = 0; bj < 2; ++bj) { const v4u t = hb[m][bj];
;                             *(GAS f32x4*)(dp + bj * 128) = (f32x4){bf_lo(t.x), bf_hi(t.x), bf_lo(t.y), bf_hi(t.y)} + acc[ai][bj][m][0]; *(GAS f32x4*)(dp + bj * 128 + 4) = (f32x4){bf_lo(t.z), bf_hi(t.z), bf_lo(t.w), bf_hi(t.w)} + acc[ai][bj][m][1]; } }
.LBB0_1241:
	v_ashrrev_i32_e32 v49, 31, v48
	v_lshl_add_u64 v[50:51], s[8:9], 0, v[50:51]
	v_lshlrev_b64 v[48:49], 12, v[48:49]
	v_lshl_add_u64 v[48:49], v[50:51], 0, v[48:49]
	s_waitcnt vmcnt(0)
	v_lshlrev_b32_e32 v50, 16, v84
	v_and_b32_e32 v51, 0xffff0000, v84
	v_lshlrev_b32_e32 v52, 16, v85
	v_and_b32_e32 v53, 0xffff0000, v85
	v_lshl_add_u64 v[48:49], v[170:171], 2, v[48:49]
	v_pk_add_f32 v[46:47], v[46:47], v[52:53]
	v_pk_add_f32 v[44:45], v[44:45], v[50:51]
	global_store_dwordx4 v[48:49], v[44:47], off nt
	s_nop 1
	v_lshlrev_b32_e32 v44, 16, v86
	v_and_b32_e32 v45, 0xffff0000, v86
	v_lshlrev_b32_e32 v46, 16, v87
	v_and_b32_e32 v47, 0xffff0000, v87
	v_pk_add_f32 v[42:43], v[42:43], v[46:47]
	v_pk_add_f32 v[40:41], v[40:41], v[44:45]
	global_store_dwordx4 v[48:49], v[40:43], off offset:16 nt
	s_nop 1
	v_lshlrev_b32_e32 v40, 16, v80
	v_and_b32_e32 v41, 0xffff0000, v80
	v_lshlrev_b32_e32 v42, 16, v81
	v_and_b32_e32 v43, 0xffff0000, v81
	v_pk_add_f32 v[38:39], v[38:39], v[42:43]
	v_pk_add_f32 v[36:37], v[36:37], v[40:41]
	global_store_dwordx4 v[48:49], v[36:39], off offset:512 nt
	s_nop 1
	v_lshlrev_b32_e32 v36, 16, v82
	v_and_b32_e32 v37, 0xffff0000, v82
	v_lshlrev_b32_e32 v38, 16, v83
	v_and_b32_e32 v39, 0xffff0000, v83
	v_pk_add_f32 v[34:35], v[34:35], v[38:39]
	v_pk_add_f32 v[32:33], v[32:33], v[36:37]
	global_store_dwordx4 v[48:49], v[32:35], off offset:528 nt

; #define GAS __attribute__((address_space(1)))
; __device__ __forceinline__ float bf_lo(unsigned u) { return __uint_as_float(u << 16); }
; __device__ __forceinline__ float bf_hi(unsigned u) { return __uint_as_float(u & 0xffff0000u); }
;     __device__ __forceinline__ void operator()(Acc& acc, const Unit& u, int wr, int wc, int fr, int fq, LAS unsigned char* lds) const {
;     ...
;             for (int m = 0; m < 4; ++m) { const int row = row0 + ai * 128 + m * 16;
;                 if (last) { GAS float* dp; bool ok = true;
;                     if (sample) dp = out + O_YS + (size_t)(row - MPAD) * 1024 + c0;
;                     else { const int b = row / LP, t = row - b * LP; ok = row < MP && t >= NMETA; dp = out + O_YP + ((size_t)b * SEQ + (t - NMETA)) * 1024 + c0; }
;                     if (ok) {
; #pragma unroll
;                         for (int bj = 0; bj < 2; ++bj) { const v4u t = hb[m][bj];
;                             *(GAS f32x4*)(dp + bj * 128) = (f32x4){bf_lo(t.x), bf_hi(t.x), bf_lo(t.y), bf_hi(t.y)} + acc[ai][bj][m][0]; *(GAS f32x4*)(dp + bj * 128 + 4) = (f32x4){bf_lo(t.z), bf_hi(t.z), bf_lo(t.w), bf_hi(t.w)} + acc[ai][bj][m][1]; } }
.LBB0_1247:
	v_ashrrev_i32_e32 v33, 31, v32
	v_lshl_add_u64 v[34:35], s[8:9], 0, v[34:35]
	v_lshlrev_b64 v[32:33], 12, v[32:33]
	v_lshl_add_u64 v[32:33], v[34:35], 0, v[32:33]
	s_waitcnt vmcnt(0)
	v_lshlrev_b32_e32 v34, 16, v76
	v_and_b32_e32 v35, 0xffff0000, v76
	v_lshlrev_b32_e32 v36, 16, v77
	v_and_b32_e32 v37, 0xffff0000, v77
	v_lshl_add_u64 v[32:33], v[170:171], 2, v[32:33]
	v_pk_add_f32 v[30:31], v[30:31], v[36:37]
	v_pk_add_f32 v[28:29], v[28:29], v[34:35]
	global_store_dwordx4 v[32:33], v[28:31], off nt
	s_nop 1
	v_lshlrev_b32_e32 v28, 16, v78
	v_and_b32_e32 v29, 0xffff0000, v78
	v_lshlrev_b32_e32 v30, 16, v79
	v_and_b32_e32 v31, 0xffff0000, v79
	v_pk_add_f32 v[26:27], v[26:27], v[30:31]
	v_pk_add_f32 v[24:25], v[24:25], v[28:29]
	global_store_dwordx4 v[32:33], v[24:27], off offset:16 nt
	s_nop 1
	v_lshlrev_b32_e32 v24, 16, v72
	v_and_b32_e32 v25, 0xffff0000, v72
	v_lshlrev_b32_e32 v26, 16, v73
	v_and_b32_e32 v27, 0xffff0000, v73
	v_pk_add_f32 v[22:23], v[22:23], v[26:27]
	v_pk_add_f32 v[20:21], v[20:21], v[24:25]
	global_store_dwordx4 v[32:33], v[20:23], off offset:512 nt
	s_nop 1
	v_lshlrev_b32_e32 v20, 16, v74
	v_and_b32_e32 v21, 0xffff0000, v74
	v_lshlrev_b32_e32 v22, 16, v75
	v_and_b32_e32 v23, 0xffff0000, v75
	v_pk_add_f32 v[18:19], v[18:19], v[22:23]
	v_pk_add_f32 v[16:17], v[16:17], v[20:21]
	global_store_dwordx4 v[32:33], v[16:19], off offset:528 nt

; #define GAS __attribute__((address_space(1)))
; __device__ __forceinline__ float bf_lo(unsigned u) { return __uint_as_float(u << 16); }
; __device__ __forceinline__ float bf_hi(unsigned u) { return __uint_as_float(u & 0xffff0000u); }
;     __device__ __forceinline__ void operator()(Acc& acc, const Unit& u, int wr, int wc, int fr, int fq, LAS unsigned char* lds) const {
;     ...
;             for (int m = 0; m < 4; ++m) { const int row = row0 + ai * 128 + m * 16;
;                 if (last) { GAS float* dp; bool ok = true;
;                     if (sample) dp = out + O_YS + (size_t)(row - MPAD) * 1024 + c0;
;                     else { const int b = row / LP, t = row - b * LP; ok = row < MP && t >= NMETA; dp = out + O_YP + ((size_t)b * SEQ + (t - NMETA)) * 1024 + c0; }
;                     if (ok) {
; #pragma unroll
;                         for (int bj = 0; bj < 2; ++bj) { const v4u t = hb[m][bj];
;                             *(GAS f32x4*)(dp + bj * 128) = (f32x4){bf_lo(t.x), bf_hi(t.x), bf_lo(t.y), bf_hi(t.y)} + acc[ai][bj][m][0]; *(GAS f32x4*)(dp + bj * 128 + 4) = (f32x4){bf_lo(t.z), bf_hi(t.z), bf_lo(t.w), bf_hi(t.w)} + acc[ai][bj][m][1]; } }
.LBB0_1253:
	v_ashrrev_i32_e32 v17, 31, v16
	v_lshl_add_u64 v[18:19], s[8:9], 0, v[18:19]
	v_lshlrev_b64 v[16:17], 12, v[16:17]
	v_lshl_add_u64 v[16:17], v[18:19], 0, v[16:17]
	s_waitcnt vmcnt(0)
	v_lshlrev_b32_e32 v18, 16, v68
	v_and_b32_e32 v19, 0xffff0000, v68
	v_lshlrev_b32_e32 v20, 16, v69
	v_and_b32_e32 v21, 0xffff0000, v69
	v_lshl_add_u64 v[16:17], v[170:171], 2, v[16:17]
	v_pk_add_f32 v[14:15], v[14:15], v[20:21]
	v_pk_add_f32 v[12:13], v[12:13], v[18:19]
	global_store_dwordx4 v[16:17], v[12:15], off nt
	s_nop 1
	v_lshlrev_b32_e32 v12, 16, v70
	v_and_b32_e32 v13, 0xffff0000, v70
	v_lshlrev_b32_e32 v14, 16, v71
	v_and_b32_e32 v15, 0xffff0000, v71
	v_pk_add_f32 v[10:11], v[10:11], v[14:15]
	v_pk_add_f32 v[8:9], v[8:9], v[12:13]
	global_store_dwordx4 v[16:17], v[8:11], off offset:16 nt
	s_nop 1
	v_lshlrev_b32_e32 v8, 16, v64
	v_and_b32_e32 v9, 0xffff0000, v64
	v_lshlrev_b32_e32 v10, 16, v65
	v_and_b32_e32 v11, 0xffff0000, v65
	v_pk_add_f32 v[6:7], v[6:7], v[10:11]
	v_pk_add_f32 v[4:5], v[4:5], v[8:9]
	global_store_dwordx4 v[16:17], v[4:7], off offset:512 nt
	s_nop 1
	v_lshlrev_b32_e32 v4, 16, v66
	v_and_b32_e32 v5, 0xffff0000, v66
	v_lshlrev_b32_e32 v6, 16, v67
	v_and_b32_e32 v7, 0xffff0000, v67
	v_pk_add_f32 v[2:3], v[2:3], v[6:7]
	v_pk_add_f32 v[0:1], v[0:1], v[4:5]
	global_store_dwordx4 v[16:17], v[0:3], off offset:528 nt
